# FoX loop rotated: next key tile's global loads (K,V^T,cf) are issued at the end of the previous iteration right after the staging registers were stored to LDS and before the barrier, instead of after
# speedup vs baseline: 1.0041x; 1.0041x over previous
; DI void fox_attn(const Params& P, int bh, int qb, unsigned char* smem, int tt) {
;     ...
;     rk0 = *(const u32x4*)kg; rk1 = *(const u32x4*)(kg + 32 * 1024);
;     rv0 = *(const u32x4*)vg; rv1 = *(const u32x4*)(vg + 32 * TSEQ);
;     if (tid < 64) rc = cf[tid] * L2E;
;     {
;         bf16_t* Ks = (bf16_t*)smem; bf16_t* VTs = Ks + 64 * 72; float* cks = (float*)(smem + 2 * 64 * 72 * 2);
;         *(u32x4*)(Ks + srow * 72 + scol) = rk0; *(u32x4*)(Ks + (srow + 32) * 72 + scol) = rk1;
;         *(u32x4*)(VTs + srow * 72 + scol) = rv0; *(u32x4*)(VTs + (srow + 32) * 72 + scol) = rv1;
;         if (tid < 64) cks[tid] = rc;
;     }
;     __syncthreads();
; #pragma unroll 1
;     for (int kt = 0; kt < ntiles; ++kt) {
;         const unsigned char* bufc = smem + (kt & 1) * BUFB;
;         const bf16_t* Ks = (const bf16_t*)bufc; const bf16_t* VTs = Ks + 64 * 72; const float* cks = (const float*)(bufc + 2 * 64 * 72 * 2);
;         const bool more = kt + 1 < ntiles;
;         if (more) {
;             const bf16_t* kg2 = kg + (size_t)(kt + 1) * 64 * 1024; const bf16_t* vg2 = vg + (kt + 1) * 64;
;             rk0 = *(const u32x4*)kg2; rk1 = *(const u32x4*)(kg2 + 32 * 1024);
;             rv0 = *(const u32x4*)vg2; rv1 = *(const u32x4*)(vg2 + 32 * TSEQ);
;             if (tid < 64) rc = cf[(kt + 1) * 64 + tid] * L2E;
;     ...
;         if (more) {
;             unsigned char* bufn = smem + ((kt + 1) & 1) * BUFB;
;             bf16_t* Kn = (bf16_t*)bufn; bf16_t* VTn = Kn + 64 * 72; float* ckn = (float*)(bufn + 2 * 64 * 72 * 2);
;             *(u32x4*)(Kn + srow * 72 + scol) = rk0; *(u32x4*)(Kn + (srow + 32) * 72 + scol) = rk1;
;             *(u32x4*)(VTn + srow * 72 + scol) = rv0; *(u32x4*)(VTn + (srow + 32) * 72 + scol) = rv1;
;             if (tid < 64) ckn[tid] = rc;
;         }
;         __syncthreads();
.LBB0_542:
	s_or_b64 exec, exec, s[2:3]
	v_mul_u32_u24_e32 v0, 0x48, v2
	v_lshlrev_b32_e32 v119, 1, v0
	v_add3_u32 v0, v131, v119, v104
	s_waitcnt vmcnt(4)
	ds_write_b128 v0, v[82:85]
	s_waitcnt vmcnt(3)
	ds_write_b128 v0, v[86:89] offset:4608
	s_waitcnt vmcnt(1)
	ds_write_b128 v0, v[90:93] offset:9216
	s_waitcnt vmcnt(0)
	ds_write_b128 v0, v[94:97] offset:13824
	s_and_saveexec_b64 s[2:3], s[0:1]
	v_lshl_add_u32 v0, v130, 2, v131
	ds_write_b32 v0, v118 offset:18432
	s_or_b64 exec, exec, s[2:3]
	v_lshlrev_b32_e32 v0, 3, v23
	v_mul_f32_e32 v121, 0x3fb8aa3b, v3
	v_lshlrev_b32_e32 v105, 2, v23
	v_lshlrev_b32_e32 v3, 2, v14
	v_lshl_add_u32 v125, v0, 1, v131
	v_sub_u32_e32 v126, 0, v0
	v_add_u32_e32 v0, v9, v22
	v_xor_b32_e32 v99, 0x80, v3
	v_sub_u32_e32 v0, v0, v105
	v_lshlrev_b32_e32 v3, 7, v8
	v_sub_u32_e32 v0, v0, v3
	v_lshlrev_b64 v[4:5], 22, v[4:5]
	v_add_u32_e32 v127, 0x780, v0
	v_lshl_or_b32 v0, v2, 11, v4
	v_lshlrev_b32_e32 v2, 1, v12
	v_and_b32_e32 v3, 7, v10
	v_and_b32_e32 v2, 0x380, v2
	v_lshlrev_b32_e32 v3, 4, v3
	v_or3_b32 v4, v0, v2, v3
	v_mov_b32_e32 v14, v1
	v_mov_b32_e32 v15, v1
	v_lshlrev_b64 v[100:101], 10, v[6:7]
	v_lshlrev_b32_e32 v122, 1, v11
	v_mul_u32_u24_e32 v124, 0x48, v22
	v_lshl_add_u64 v[108:109], s[10:11], 0, v[4:5]
	v_mov_b32_e32 v0, v1
	v_mov_b32_e32 v2, v1
	v_mov_b32_e32 v3, v1
	v_mov_b32_e32 v4, v1
	v_mov_b32_e32 v5, v1
	v_mov_b32_e32 v6, v1
	v_mov_b32_e32 v7, v1
	v_mov_b32_e32 v8, v1
	v_mov_b32_e32 v9, v1
	v_mov_b32_e32 v10, v1
	v_mov_b32_e32 v11, v1
	v_mov_b32_e32 v12, v1
	v_mov_b32_e32 v13, v1
	v_mov_b64_e32 v[32:33], v[14:15]
	v_mov_b64_e32 v[30:31], v[12:13]
	v_mov_b64_e32 v[28:29], v[10:11]
	v_mov_b64_e32 v[26:27], v[8:9]
	v_mov_b64_e32 v[24:25], v[6:7]
	v_mov_b64_e32 v[22:23], v[4:5]
	v_mov_b64_e32 v[20:21], v[2:3]
	v_mov_b64_e32 v[18:19], v[0:1]
	v_mov_b64_e32 v[16:17], v[14:15]
	v_add_u32_e32 v123, 2, v122
	s_mov_b32 s47, 0
	v_mov_b32_e32 v120, 0
	v_mov_b32_e32 v128, 0xf149f2ca
	s_mov_b32 s34, 64
	s_mov_b64 s[30:31], 0
	v_mov_b64_e32 v[14:15], v[12:13]
	v_mov_b64_e32 v[12:13], v[10:11]
	v_mov_b64_e32 v[10:11], v[8:9]
	v_mov_b64_e32 v[8:9], v[6:7]
	v_mov_b64_e32 v[6:7], v[4:5]
	v_mov_b64_e32 v[4:5], v[2:3]
	v_mov_b64_e32 v[2:3], v[0:1]
	s_mov_b64 s[38:39], exec
	s_mov_b32 s35, s14
	v_add_co_u32_e32 v188, vcc, 0xffff0000, v108
	v_lshl_add_u64 v[186:187], s[34:35], 1, v[106:107]
	s_nop 0
	v_addc_co_u32_e32 v189, vcc, -1, v109, vcc
	global_load_dwordx4 v[82:85], v[188:189], off
	global_load_dwordx4 v[86:89], v[108:109], off
	global_load_dwordx4 v[90:93], v[186:187], off
	v_add_co_u32_e32 v186, vcc, 0x20000, v186
	s_nop 1
	v_addc_co_u32_e32 v187, vcc, 0, v187, vcc
	global_load_dwordx4 v[94:97], v[186:187], off
	s_and_b64 exec, exec, s[0:1]
	s_cbranch_execz .Lfox_pf0_done
	v_add_u32_e32 v186, s34, v130
	v_mov_b32_e32 v187, 0
	v_lshl_add_u64 v[186:187], v[186:187], 2, v[102:103]
	global_load_dword v118, v[186:187], off
.Lfox_pf0_done:
	s_or_b64 exec, exec, s[38:39]
	s_waitcnt lgkmcnt(0)
	s_barrier
	s_branch .LBB0_546
.LBB0_545:
	s_or_b64 exec, exec, s[36:37]
	v_pk_add_f32 v[44:45], v[44:45], 0 op_sel_hi:[1,0]
	s_add_i32 s34, s34, 64
	v_pk_add_f32 v[44:45], v[46:47], v[44:45]
	v_cmp_eq_u32_e32 vcc, s47, v123
	v_pk_add_f32 v[44:45], v[48:49], v[44:45]
	v_subrev_u32_e32 v127, 64, v127
	v_pk_add_f32 v[44:45], v[50:51], v[44:45]
	s_or_b64 s[30:31], vcc, s[30:31]
	v_pk_add_f32 v[44:45], v[54:55], v[44:45]
	v_lshl_add_u64 v[108:109], v[108:109], 0, s[18:19]
	v_pk_add_f32 v[44:45], v[58:59], v[44:45]
	s_add_u32 s98, s47, 1
	v_cmp_lt_u32_e64 s[100:101], s98, v123
	s_and_saveexec_b64 s[38:39], s[100:101]
	s_cbranch_execz .Lfox_pf_done
	s_mov_b32 s35, s14
	v_add_co_u32_e32 v188, vcc, 0xffff0000, v108
	v_lshl_add_u64 v[186:187], s[34:35], 1, v[106:107]
	s_nop 0
	v_addc_co_u32_e32 v189, vcc, -1, v109, vcc
	global_load_dwordx4 v[82:85], v[188:189], off
	global_load_dwordx4 v[86:89], v[108:109], off
	global_load_dwordx4 v[90:93], v[186:187], off
	v_add_co_u32_e32 v186, vcc, 0x20000, v186
	s_nop 1
	v_addc_co_u32_e32 v187, vcc, 0, v187, vcc
	global_load_dwordx4 v[94:97], v[186:187], off
	s_and_b64 exec, exec, s[0:1]
	s_cbranch_execz .Lfox_pf_done
	v_add_u32_e32 v186, s34, v130
	v_mov_b32_e32 v187, 0
	v_lshl_add_u64 v[186:187], v[186:187], 2, v[102:103]
	global_load_dword v118, v[186:187], off
.Lfox_pf_done:
	s_or_b64 exec, exec, s[38:39]
	s_waitcnt lgkmcnt(0)
	v_pk_add_f32 v[44:45], v[64:65], v[44:45]
	s_barrier
	v_pk_add_f32 v[44:45], v[56:57], v[44:45]
	s_nop 0
	v_pk_add_f32 v[44:45], v[62:63], v[44:45]
	s_nop 0
	v_pk_add_f32 v[44:45], v[52:53], v[44:45]
	s_nop 0
	v_pk_add_f32 v[44:45], v[60:61], v[44:45]
	s_nop 0
	v_pk_add_f32 v[38:39], v[38:39], v[44:45]
	s_nop 0
	v_pk_add_f32 v[38:39], v[42:43], v[38:39]
	s_nop 0
	v_pk_add_f32 v[36:37], v[36:37], v[38:39]
	s_nop 0
	v_pk_add_f32 v[36:37], v[40:41], v[36:37]
	s_nop 0
	v_pk_add_f32 v[34:35], v[34:35], v[36:37]
	s_nop 0
	v_add_f32_e32 v0, v34, v35
	v_add_f32_e32 v120, v120, v0
	s_andn2_b64 exec, exec, s[30:31]
	s_cbranch_execz .LBB0_557

; #define MFMA32(a, b, c) __builtin_amdgcn_mfma_f32_32x32x16_bf16((a), (b), (c), 0, 0, 0)
; DI void fox_attn(const Params& P, int bh, int qb, unsigned char* smem, int tt) {
;     ...
;         f32x16 sacc[2];
;         f32x4 ckv[2][4];
;         {
;             bf16x8 kf[2][4];
; #pragma unroll
;             for (int mt = 0; mt < 2; ++mt)
; #pragma unroll
;                 for (int ks = 0; ks < 4; ++ks) kf[mt][ks] = *(const bf16x8*)(Ks + (mt * 32 + r) * 72 + ks * 16 + h2 * 8);
; #pragma unroll
;             for (int mt = 0; mt < 2; ++mt)
; #pragma unroll
;                 for (int g = 0; g < 4; ++g) ckv[mt][g] = *(const f32x4*)(cks + mt * 32 + 8 * g + 4 * h2);
; #pragma unroll
;             for (int e = 0; e < 16; ++e) { sacc[0][e] = 0.f; sacc[1][e] = 0.f; }
;             __builtin_amdgcn_sched_barrier(0);
; #pragma unroll
;             for (int ks = 0; ks < 4; ++ks) { sacc[0] = MFMA32(kf[0][ks], Qf[ks], sacc[0]); sacc[1] = MFMA32(kf[1][ks], Qf[ks], sacc[1]); }
;         }
;         const bool diag = kt >= ntiles - 2;
;         float mx = -1e30f;
;         {
;             const f32x2v csc = {0.125f * L2E, 0.125f * L2E};
; #pragma unroll
;             for (int mt = 0; mt < 2; ++mt)
; #pragma unroll
;                 for (int g = 0; g < 4; ++g) {
;                     const f32x4 ck4 = ckv[mt][g];
;                     const f32x2v c01 = {ck4[0], ck4[1]}, c23 = {ck4[2], ck4[3]};
;                     const f32x2v a01 = {sacc[mt][4 * g], sacc[mt][4 * g + 1]}, a23 = {sacc[mt][4 * g + 2], sacc[mt][4 * g + 3]};
;                     const f32x2v s01 = a01 * csc - c01, s23 = a23 * csc - c23;
;                     sacc[mt][4 * g] = s01.x; sacc[mt][4 * g + 1] = s01.y; sacc[mt][4 * g + 2] = s23.x; sacc[mt][4 * g + 3] = s23.y;
;                     mx = fmaxf(fmaxf(mx, s01.x), s01.y); mx = fmaxf(fmaxf(mx, s23.x), s23.y);
;                 }
;         }
;         if (diag) {
;             mx = -1e30f;
;             const int qrel = q - kt * 64 - 4 * h2;
; #pragma unroll
;             for (int mt = 0; mt < 2; ++mt)
; #pragma unroll
;                 for (int e = 0; e < 16; ++e) {
;                     const int krel = mt * 32 + (e & 3) + 8 * (e >> 2);
;                     const float sv = (krel > qrel) ? -1e30f : sacc[mt][e];
;                     sacc[mt][e] = sv;
;                     mx = fmaxf(mx, sv);
;                 }
;         }
.LBB0_550:
	s_bitcmp1_b32 s56, 0
	s_cselect_b32 s35, 0x4900, 0
	v_add_u32_e32 v0, s35, v125
	v_lshl_add_u32 v42, v124, 1, v0
	ds_read_b128 v[34:37], v42
	ds_read_b128 v[110:113], v42 offset:32
	ds_read_b128 v[114:117], v42 offset:64
	ds_read_b128 v[132:135], v42 offset:96
	ds_read_b128 v[38:41], v42 offset:4608
	ds_read_b128 v[136:139], v42 offset:4640
	ds_read_b128 v[140:143], v42 offset:4672
	ds_read_b128 v[144:147], v42 offset:4704
	ds_read_b128 v[148:151], v0 offset:18432
	ds_read_b128 v[152:155], v0 offset:18464
	ds_read_b128 v[156:159], v0 offset:18496
	ds_read_b128 v[160:163], v0 offset:18528
	ds_read_b128 v[170:173], v0 offset:18560
	ds_read_b128 v[174:177], v0 offset:18592
	ds_read_b128 v[178:181], v0 offset:18624
	ds_read_b128 v[182:185], v0 offset:18656
	s_waitcnt lgkmcnt(14)
	v_mfma_f32_32x32x16_bf16 v[50:65], v[34:37], v[78:81], 0
	v_cmp_ge_u32_e32 vcc, s56, v122
	s_waitcnt lgkmcnt(11)
	v_mfma_f32_32x32x16_bf16 v[34:49], v[38:41], v[78:81], 0
	v_mfma_f32_32x32x16_bf16 v[50:65], v[110:113], v[66:69], v[50:65]
	v_mfma_f32_32x32x16_bf16 v[50:65], v[114:117], v[70:73], v[50:65]
	s_waitcnt lgkmcnt(10)
	v_mfma_f32_32x32x16_bf16 v[34:49], v[136:139], v[66:69], v[34:49]
	v_mfma_f32_32x32x16_bf16 v[50:65], v[132:135], v[74:77], v[50:65]
	s_waitcnt lgkmcnt(9)
	v_mfma_f32_32x32x16_bf16 v[34:49], v[140:143], v[70:73], v[34:49]
	s_waitcnt lgkmcnt(7)
	s_nop 8
	v_fma_f32 v110, v50, s16, -v148
	v_fma_f32 v111, v51, s16, -v149
	v_fma_f32 v50, v52, s16, -v150
	v_fma_f32 v51, v53, s16, -v151
	v_max3_f32 v52, v110, s17, v111
	v_max3_f32 v52, v52, v50, v51
	s_waitcnt lgkmcnt(6)
	v_pk_fma_f32 v[114:115], v[54:55], s[16:17], v[152:153] op_sel_hi:[1,0,1] neg_lo:[0,0,1] neg_hi:[0,0,1]
	v_pk_fma_f32 v[54:55], v[56:57], s[16:17], v[154:155] op_sel_hi:[1,0,1] neg_lo:[0,0,1] neg_hi:[0,0,1]
	v_max3_f32 v52, v52, v114, v115
	v_mfma_f32_32x32x16_bf16 v[34:49], v[144:147], v[74:77], v[34:49]
	v_max3_f32 v52, v52, v54, v55
	s_waitcnt lgkmcnt(5)
	v_fma_f32 v112, v58, s16, -v156
	v_fma_f32 v113, v59, s16, -v157
	v_fma_f32 v58, v60, s16, -v158
	v_fma_f32 v59, v61, s16, -v159
	v_max3_f32 v52, v52, v112, v113
	v_max3_f32 v52, v52, v58, v59
	s_waitcnt lgkmcnt(4)
	v_pk_fma_f32 v[116:117], v[62:63], s[16:17], v[160:161] op_sel_hi:[1,0,1] neg_lo:[0,0,1] neg_hi:[0,0,1]
	v_pk_fma_f32 v[56:57], v[64:65], s[16:17], v[162:163] op_sel_hi:[1,0,1] neg_lo:[0,0,1] neg_hi:[0,0,1]
	v_max3_f32 v52, v52, v116, v117
	v_max3_f32 v60, v52, v56, v57
	s_waitcnt lgkmcnt(3)
	v_pk_fma_f32 v[62:63], v[34:35], s[16:17], v[170:171] op_sel_hi:[1,0,1] neg_lo:[0,0,1] neg_hi:[0,0,1]
	v_pk_fma_f32 v[52:53], v[36:37], s[16:17], v[172:173] op_sel_hi:[1,0,1] neg_lo:[0,0,1] neg_hi:[0,0,1]
	v_max3_f32 v34, v60, v62, v63
	v_max3_f32 v34, v34, v52, v53
	s_waitcnt lgkmcnt(2)
	v_pk_fma_f32 v[60:61], v[38:39], s[16:17], v[174:175] op_sel_hi:[1,0,1] neg_lo:[0,0,1] neg_hi:[0,0,1]
	v_pk_fma_f32 v[38:39], v[40:41], s[16:17], v[176:177] op_sel_hi:[1,0,1] neg_lo:[0,0,1] neg_hi:[0,0,1]
	v_max3_f32 v34, v34, v60, v61
	v_max3_f32 v34, v34, v38, v39
	s_waitcnt lgkmcnt(1)
	v_pk_fma_f32 v[42:43], v[42:43], s[16:17], v[178:179] op_sel_hi:[1,0,1] neg_lo:[0,0,1] neg_hi:[0,0,1]
	v_pk_fma_f32 v[36:37], v[44:45], s[16:17], v[180:181] op_sel_hi:[1,0,1] neg_lo:[0,0,1] neg_hi:[0,0,1]
	v_max3_f32 v34, v34, v42, v43
	v_max3_f32 v44, v34, v36, v37
	s_waitcnt lgkmcnt(0)
	v_pk_fma_f32 v[40:41], v[46:47], s[16:17], v[182:183] op_sel_hi:[1,0,1] neg_lo:[0,0,1] neg_hi:[0,0,1]
	v_pk_fma_f32 v[34:35], v[48:49], s[16:17], v[184:185] op_sel_hi:[1,0,1] neg_lo:[0,0,1] neg_hi:[0,0,1]
	v_max3_f32 v44, v44, v40, v41
	v_max3_f32 v44, v44, v34, v35
	s_and_saveexec_b64 s[36:37], vcc
	s_cbranch_execz .LBB0_552
	v_cmp_lt_i32_e32 vcc, -1, v127
	s_nop 1
	v_cndmask_b32_e32 v110, v167, v110, vcc
	v_cmp_lt_i32_e32 vcc, 0, v127
	s_nop 1
	v_cndmask_b32_e32 v111, v167, v111, vcc
	v_cmp_lt_i32_e32 vcc, 1, v127
	v_max3_f32 v44, v110, s17, v111
	s_nop 0
	v_cndmask_b32_e32 v50, v167, v50, vcc
	v_cmp_lt_i32_e32 vcc, 2, v127
	s_nop 1
	v_cndmask_b32_e32 v51, v167, v51, vcc
	v_cmp_lt_i32_e32 vcc, 7, v127
	v_max3_f32 v44, v44, v50, v51
	s_nop 0
	v_cndmask_b32_e32 v114, v167, v114, vcc
	v_cmp_lt_i32_e32 vcc, 8, v127
	s_nop 1
	v_cndmask_b32_e32 v115, v167, v115, vcc
	v_cmp_lt_i32_e32 vcc, 9, v127
	v_max3_f32 v44, v44, v114, v115
	s_nop 0
	v_cndmask_b32_e32 v54, v167, v54, vcc
	v_cmp_lt_i32_e32 vcc, 10, v127
	s_nop 1
	v_cndmask_b32_e32 v55, v167, v55, vcc
	v_cmp_lt_i32_e32 vcc, 15, v127
	v_max3_f32 v44, v44, v54, v55
	s_nop 0
	v_cndmask_b32_e32 v112, v167, v112, vcc
	v_cmp_lt_i32_e32 vcc, 16, v127
	s_nop 1
	v_cndmask_b32_e32 v113, v167, v113, vcc
	v_cmp_lt_i32_e32 vcc, 17, v127
	v_max3_f32 v44, v44, v112, v113
	s_nop 0
	v_cndmask_b32_e32 v58, v167, v58, vcc
	v_cmp_lt_i32_e32 vcc, 18, v127
	s_nop 1
	v_cndmask_b32_e32 v59, v167, v59, vcc
	v_cmp_lt_i32_e32 vcc, 23, v127
	v_max3_f32 v44, v44, v58, v59
	s_nop 0
	v_cndmask_b32_e32 v116, v167, v116, vcc
	v_cmp_lt_i32_e32 vcc, 24, v127
	s_nop 1
	v_cndmask_b32_e32 v117, v167, v117, vcc
	v_cmp_lt_i32_e32 vcc, 25, v127
	v_max3_f32 v44, v44, v116, v117
	s_nop 0
	v_cndmask_b32_e32 v56, v167, v56, vcc
	v_cmp_lt_i32_e32 vcc, 26, v127
	s_nop 1
	v_cndmask_b32_e32 v57, v167, v57, vcc
	v_cmp_lt_i32_e32 vcc, 31, v127
	v_max3_f32 v44, v44, v56, v57
	s_nop 0
	v_cndmask_b32_e32 v62, v167, v62, vcc
	v_cmp_lt_i32_e32 vcc, 32, v127
	s_nop 1
	v_cndmask_b32_e32 v63, v167, v63, vcc
	v_cmp_lt_i32_e32 vcc, 33, v127
	v_max3_f32 v44, v44, v62, v63
	s_nop 0
	v_cndmask_b32_e32 v52, v167, v52, vcc
	v_cmp_lt_i32_e32 vcc, 34, v127
	s_nop 1
	v_cndmask_b32_e32 v53, v167, v53, vcc
	v_cmp_lt_i32_e32 vcc, 39, v127
	v_max3_f32 v44, v44, v52, v53
	s_nop 0
	v_cndmask_b32_e32 v60, v167, v60, vcc
	v_cmp_lt_i32_e32 vcc, 40, v127
	s_nop 1
	v_cndmask_b32_e32 v61, v167, v61, vcc
	v_cmp_lt_i32_e32 vcc, 41, v127
	v_max3_f32 v44, v44, v60, v61
	s_nop 0
	v_cndmask_b32_e32 v38, v167, v38, vcc
	v_cmp_lt_i32_e32 vcc, 42, v127
	s_nop 1
	v_cndmask_b32_e32 v39, v167, v39, vcc
	v_cmp_lt_i32_e32 vcc, 47, v127
	v_max3_f32 v44, v44, v38, v39
	s_nop 0
	v_cndmask_b32_e32 v42, v167, v42, vcc
	v_cmp_lt_i32_e32 vcc, 48, v127
	s_nop 1
	v_cndmask_b32_e32 v43, v167, v43, vcc
	v_cmp_lt_i32_e32 vcc, 49, v127
	v_max3_f32 v44, v44, v42, v43
	s_nop 0
	v_cndmask_b32_e32 v36, v167, v36, vcc
	v_cmp_lt_i32_e32 vcc, 50, v127
	s_nop 1
	v_cndmask_b32_e32 v37, v167, v37, vcc
	v_cmp_lt_i32_e32 vcc, 55, v127
	v_max3_f32 v44, v44, v36, v37
	s_nop 0
	v_cndmask_b32_e32 v40, v167, v40, vcc
	v_cmp_lt_i32_e32 vcc, 56, v127
	s_nop 1
	v_cndmask_b32_e32 v41, v167, v41, vcc
	v_cmp_lt_i32_e32 vcc, 57, v127
	v_max3_f32 v44, v44, v40, v41
	s_nop 0
	v_cndmask_b32_e32 v34, v167, v34, vcc
	v_cmp_lt_i32_e32 vcc, 58, v127
	s_nop 1
	v_cndmask_b32_e32 v35, v167, v35, vcc
	v_max3_f32 v44, v44, v34, v35

; __global__ void __launch_bounds__(512, 2) fwd_mega(Params P) {
;     cg::grid_group grid = cg::this_grid();
	.amdhsa_kernel _Z8fwd_mega6Params
		.amdhsa_group_segment_fixed_size 0
		.amdhsa_private_segment_fixed_size 0
		.amdhsa_kernarg_size 440
		.amdhsa_user_sgpr_count 2
		.amdhsa_user_sgpr_dispatch_ptr 0
		.amdhsa_user_sgpr_queue_ptr 0
		.amdhsa_user_sgpr_kernarg_segment_ptr 1
		.amdhsa_user_sgpr_dispatch_id 0
		.amdhsa_user_sgpr_kernarg_preload_length 0
		.amdhsa_user_sgpr_kernarg_preload_offset 0
		.amdhsa_user_sgpr_private_segment_size 0
		.amdhsa_uses_dynamic_stack 0
		.amdhsa_enable_private_segment 0
		.amdhsa_system_sgpr_workgroup_id_x 1
		.amdhsa_system_sgpr_workgroup_id_y 0
		.amdhsa_system_sgpr_workgroup_id_z 0
		.amdhsa_system_sgpr_workgroup_info 0
		.amdhsa_system_vgpr_workitem_id 2
		.amdhsa_next_free_vgpr 256
		.amdhsa_next_free_sgpr 102
		.amdhsa_accum_offset 256
		.amdhsa_reserve_vcc 1
		.amdhsa_float_round_mode_32 0
		.amdhsa_float_round_mode_16_64 0
		.amdhsa_float_denorm_mode_32 3
		.amdhsa_float_denorm_mode_16_64 3
		.amdhsa_dx10_clamp 1
		.amdhsa_ieee_mode 1
		.amdhsa_fp16_overflow 0
		.amdhsa_tg_split 0
		.amdhsa_exception_fp_ieee_invalid_op 0
		.amdhsa_exception_fp_denorm_src 0
		.amdhsa_exception_fp_ieee_div_zero 0
		.amdhsa_exception_fp_ieee_overflow 0
		.amdhsa_exception_fp_ieee_underflow 0
		.amdhsa_exception_fp_ieee_inexact 0
		.amdhsa_exception_int_div_zero 0
	.end_amdhsa_kernel

; __global__ void __launch_bounds__(512, 2) fwd_mega(Params P) {
;     cg::grid_group grid = cg::this_grid();
amdhsa.kernels:
  - .agpr_count:     0
    .args:
      - .offset:         0
        .size:           184
        .value_kind:     by_value
      - .offset:         184
        .size:           4
        .value_kind:     hidden_block_count_x
      - .offset:         188
        .size:           4
        .value_kind:     hidden_block_count_y
      - .offset:         192
        .size:           4
        .value_kind:     hidden_block_count_z
      - .offset:         196
        .size:           2
        .value_kind:     hidden_group_size_x
      - .offset:         198
        .size:           2
        .value_kind:     hidden_group_size_y
      - .offset:         200
        .size:           2
        .value_kind:     hidden_group_size_z
      - .offset:         202
        .size:           2
        .value_kind:     hidden_remainder_x
      - .offset:         204
        .size:           2
        .value_kind:     hidden_remainder_y
      - .offset:         206
        .size:           2
        .value_kind:     hidden_remainder_z
      - .offset:         224
        .size:           8
        .value_kind:     hidden_global_offset_x
      - .offset:         232
        .size:           8
        .value_kind:     hidden_global_offset_y
      - .offset:         240
        .size:           8
        .value_kind:     hidden_global_offset_z
      - .offset:         248
        .size:           2
        .value_kind:     hidden_grid_dims
      - .offset:         272
        .size:           8
        .value_kind:     hidden_multigrid_sync_arg
      - .offset:         304
        .size:           4
        .value_kind:     hidden_dynamic_lds_size
    .group_segment_fixed_size: 0
    .kernarg_segment_align: 8
    .kernarg_segment_size: 440
    .language:       OpenCL C
    .language_version:
      - 2
      - 0
    .max_flat_workgroup_size: 512
    .name:           _Z8fwd_mega6Params
    .private_segment_fixed_size: 0
    .sgpr_count:     108
    .sgpr_spill_count: 50
    .symbol:         _Z8fwd_mega6Params.kd
    .uniform_work_group_size: 1
    .uses_dynamic_stack: false
    .vgpr_count:     256
    .vgpr_spill_count: 0
    .wavefront_size: 64
